# v7 + P3 mLSTM segment-local unit: all 32 V-fragment reads of a chunk requested ahead (v160..v223) instead of one LDS round trip per MFMA
# speedup vs baseline: 1.0052x; 1.0042x over previous
.LBB0_485:
	s_or_b64 exec, exec, s[18:19]
	v_add_f32_e32 v24, v87, v128
	v_max_f32_e32 v25, v129, v129
	v_max_f32_e32 v25, v24, v25
	v_sub_f32_e32 v26, v129, v25
	v_sub_f32_e32 v24, v24, v25
	v_mul_f32_e32 v26, 0x3fb8aa3b, v26
	v_mul_f32_e32 v24, 0x3fb8aa3b, v24
	v_exp_f32_e32 v26, v26
	v_exp_f32_e32 v24, v24
	v_add_u32_e32 v129, 0x13800, v145
	s_waitcnt lgkmcnt(0)
	v_pk_mul_f32 v[28:29], v[26:27], v[56:57] op_sel_hi:[0,1]
	v_pk_fma_f32 v[124:125], v[124:125], v[24:25], v[28:29] op_sel_hi:[1,0,1]
	v_pk_mul_f32 v[28:29], v[26:27], v[52:53] op_sel_hi:[0,1]
	v_pk_mul_f32 v[18:19], v[26:27], v[18:19] op_sel_hi:[0,1]
	v_pk_fma_f32 v[120:121], v[120:121], v[24:25], v[28:29] op_sel_hi:[1,0,1]
	v_pk_mul_f32 v[28:29], v[26:27], v[48:49] op_sel_hi:[0,1]
	v_pk_fma_f32 v[74:75], v[74:75], v[24:25], v[18:19] op_sel_hi:[1,0,1]
	v_add_f32_e32 v18, v25, v22
	v_max_f32_e32 v19, v23, v23
	v_pk_fma_f32 v[116:117], v[116:117], v[24:25], v[28:29] op_sel_hi:[1,0,1]
	v_pk_mul_f32 v[28:29], v[26:27], v[44:45] op_sel_hi:[0,1]
	v_max_f32_e32 v87, v18, v19
	v_pk_fma_f32 v[112:113], v[112:113], v[24:25], v[28:29] op_sel_hi:[1,0,1]
	v_pk_mul_f32 v[28:29], v[26:27], v[40:41] op_sel_hi:[0,1]
	v_sub_f32_e32 v18, v18, v87
	v_pk_fma_f32 v[108:109], v[108:109], v[24:25], v[28:29] op_sel_hi:[1,0,1]
	v_pk_mul_f32 v[28:29], v[26:27], v[36:37] op_sel_hi:[0,1]
	v_mul_f32_e32 v18, 0x3fb8aa3b, v18
	v_pk_fma_f32 v[104:105], v[104:105], v[24:25], v[28:29] op_sel_hi:[1,0,1]
	v_pk_mul_f32 v[28:29], v[26:27], v[32:33] op_sel_hi:[0,1]
	v_pk_mul_f32 v[30:31], v[26:27], v[30:31] op_sel_hi:[0,1]
	v_exp_f32_e32 v78, v18
	v_sub_f32_e32 v18, v23, v87
	v_pk_mul_f32 v[54:55], v[26:27], v[54:55] op_sel_hi:[0,1]
	v_pk_mul_f32 v[50:51], v[26:27], v[50:51] op_sel_hi:[0,1]
	v_pk_mul_f32 v[46:47], v[26:27], v[46:47] op_sel_hi:[0,1]
	v_pk_mul_f32 v[42:43], v[26:27], v[42:43] op_sel_hi:[0,1]
	v_pk_mul_f32 v[38:39], v[26:27], v[38:39] op_sel_hi:[0,1]
	v_pk_mul_f32 v[34:35], v[26:27], v[34:35] op_sel_hi:[0,1]
	v_pk_fma_f32 v[102:103], v[102:103], v[24:25], v[30:31] op_sel_hi:[1,0,1]
	v_pk_fma_f32 v[100:101], v[100:101], v[24:25], v[28:29] op_sel_hi:[1,0,1]
	v_pk_mul_f32 v[28:29], v[26:27], v[60:61] op_sel_hi:[0,1]
	v_pk_mul_f32 v[30:31], v[26:27], v[58:59] op_sel_hi:[0,1]
	v_pk_mul_f32 v[20:21], v[26:27], v[20:21] op_sel_hi:[0,1]
	v_mul_f32_e32 v18, 0x3fb8aa3b, v18
	v_pk_fma_f32 v[126:127], v[126:127], v[24:25], v[54:55] op_sel_hi:[1,0,1]
	v_pk_fma_f32 v[122:123], v[122:123], v[24:25], v[50:51] op_sel_hi:[1,0,1]
	v_pk_fma_f32 v[118:119], v[118:119], v[24:25], v[46:47] op_sel_hi:[1,0,1]
	v_pk_fma_f32 v[114:115], v[114:115], v[24:25], v[42:43] op_sel_hi:[1,0,1]
	v_pk_fma_f32 v[110:111], v[110:111], v[24:25], v[38:39] op_sel_hi:[1,0,1]
	v_pk_fma_f32 v[106:107], v[106:107], v[24:25], v[34:35] op_sel_hi:[1,0,1]
	v_pk_fma_f32 v[96:97], v[96:97], v[24:25], v[30:31] op_sel_hi:[1,0,1]
	v_pk_fma_f32 v[98:99], v[98:99], v[24:25], v[28:29] op_sel_hi:[1,0,1]
	v_pk_fma_f32 v[76:77], v[76:77], v[24:25], v[20:21] op_sel_hi:[1,0,1]
	v_exp_f32_e32 v86, v18
	s_barrier
	ds_read_b128 v[18:21], v129
	ds_read_b128 v[22:25], v129 offset:16
	ds_read_b64_tr_b16 v[26:27], v137 offset:45056
	ds_read_b64_tr_b16 v[28:29], v137 offset:46144
	v_add_u32_e32 v128, v148, v149
	ds_read_b64_tr_b16 v[160:161], v128 offset:62464
	ds_read_b64_tr_b16 v[162:163], v128 offset:63552
	ds_read_b64_tr_b16 v[164:165], v128 offset:62496
	ds_read_b64_tr_b16 v[166:167], v128 offset:63584
	ds_read_b64_tr_b16 v[168:169], v128 offset:62528
	ds_read_b64_tr_b16 v[170:171], v128 offset:63616
	ds_read_b64_tr_b16 v[172:173], v128 offset:62560
	ds_read_b64_tr_b16 v[174:175], v128 offset:63648
	ds_read_b64_tr_b16 v[176:177], v128 offset:62592
	ds_read_b64_tr_b16 v[178:179], v128 offset:63680
	s_add_u32 s16, s16, 0x20000
	s_addc_u32 s17, s17, 0
	s_waitcnt lgkmcnt(11)
	v_lshlrev_b32_e32 v30, 16, v26
	v_and_b32_e32 v31, 0xffff0000, v26
	v_pk_mul_f32 v[18:19], v[18:19], v[30:31]
	s_mov_b64 s[18:19], 0x800
	v_cvt_pk_bf16_f32 v58, v18, v19
	v_lshlrev_b32_e32 v18, 16, v27
	v_and_b32_e32 v19, 0xffff0000, v27
	v_pk_mul_f32 v[18:19], v[20:21], v[18:19]
	s_add_i32 s20, s20, 16
	v_cvt_pk_bf16_f32 v59, v18, v19
	s_waitcnt lgkmcnt(10)
	v_lshlrev_b32_e32 v18, 16, v28
	v_and_b32_e32 v19, 0xffff0000, v28
	v_pk_mul_f32 v[18:19], v[22:23], v[18:19]
	v_lshl_add_u64 v[90:91], v[90:91], 0, s[18:19]
	v_cvt_pk_bf16_f32 v60, v18, v19
	v_lshlrev_b32_e32 v18, 16, v29
	v_and_b32_e32 v19, 0xffff0000, v29
	v_pk_mul_f32 v[18:19], v[24:25], v[18:19]
	s_cmp_eq_u32 s16, 0x60000
	v_cvt_pk_bf16_f32 v61, v18, v19
	ds_read_b64_tr_b16 v[180:181], v128 offset:62624
	ds_read_b64_tr_b16 v[182:183], v128 offset:63712
	ds_read_b64_tr_b16 v[184:185], v128 offset:62656
	ds_read_b64_tr_b16 v[186:187], v128 offset:63744
	ds_read_b64_tr_b16 v[188:189], v128 offset:62688
	ds_read_b64_tr_b16 v[190:191], v128 offset:63776
	s_waitcnt lgkmcnt(14)
	v_mfma_f32_16x16x32_bf16 v[50:53], v[58:61], v[160:163], 0
	ds_read_b64_tr_b16 v[192:193], v136 offset:62464
	ds_read_b64_tr_b16 v[194:195], v136 offset:63552
	s_waitcnt lgkmcnt(12)
	v_mfma_f32_16x16x32_bf16 v[46:49], v[58:61], v[168:171], 0
	ds_read_b64_tr_b16 v[196:197], v136 offset:62496
	ds_read_b64_tr_b16 v[198:199], v136 offset:63584
	s_waitcnt lgkmcnt(12)
	v_mfma_f32_16x16x32_bf16 v[42:45], v[58:61], v[172:175], 0
	ds_read_b64_tr_b16 v[200:201], v136 offset:62528
	ds_read_b64_tr_b16 v[202:203], v136 offset:63616
	s_waitcnt lgkmcnt(12)
	v_mfma_f32_16x16x32_bf16 v[38:41], v[58:61], v[176:179], 0
	ds_read_b64_tr_b16 v[204:205], v136 offset:62560
	ds_read_b64_tr_b16 v[206:207], v136 offset:63648
	s_waitcnt lgkmcnt(12)
	v_mfma_f32_16x16x32_bf16 v[34:37], v[58:61], v[180:183], 0
	ds_read_b64_tr_b16 v[208:209], v136 offset:62592
	ds_read_b64_tr_b16 v[210:211], v136 offset:63680
	s_waitcnt lgkmcnt(12)
	v_mfma_f32_16x16x32_bf16 v[30:33], v[58:61], v[184:187], 0
	ds_read_b64_tr_b16 v[212:213], v136 offset:62624
	ds_read_b64_tr_b16 v[214:215], v136 offset:63712
	s_waitcnt lgkmcnt(12)
	v_mfma_f32_16x16x32_bf16 v[26:29], v[58:61], v[188:191], 0
	ds_read_b64_tr_b16 v[216:217], v136 offset:62656
	ds_read_b64_tr_b16 v[218:219], v136 offset:63744
	ds_read_b64_tr_b16 v[220:221], v136 offset:62688
	ds_read_b64_tr_b16 v[222:223], v136 offset:63776
	v_mov_b64_e32 v[20:21], s[6:7]
	v_mov_b64_e32 v[18:19], s[4:5]
	v_mfma_f32_16x16x32_bf16 v[54:57], v[58:61], v[164:167], 0
	s_nop 0
	v_mfma_f32_16x16x32_bf16 v[22:25], v[58:61], v[18:21], 0
	ds_read_b128 v[62:65], v129 offset:128
	ds_read_b128 v[58:61], v129 offset:144
	ds_read_b64_tr_b16 v[130:131], v137 offset:53760
	ds_read_b64_tr_b16 v[132:133], v137 offset:54848
	s_waitcnt lgkmcnt(1)
	v_lshlrev_b32_e32 v150, 16, v130
	v_and_b32_e32 v151, 0xffff0000, v130
	v_lshlrev_b32_e32 v130, 16, v131
	v_and_b32_e32 v131, 0xffff0000, v131
	v_pk_mul_f32 v[62:63], v[62:63], v[150:151]
	v_pk_mul_f32 v[64:65], v[64:65], v[130:131]
	v_cvt_pk_bf16_f32 v62, v62, v63
	v_cvt_pk_bf16_f32 v63, v64, v65
	s_waitcnt lgkmcnt(0)
	v_lshlrev_b32_e32 v64, 16, v132
	v_and_b32_e32 v65, 0xffff0000, v132
	v_pk_mul_f32 v[58:59], v[58:59], v[64:65]
	s_nop 0
	v_cvt_pk_bf16_f32 v64, v58, v59
	v_lshlrev_b32_e32 v58, 16, v133
	v_and_b32_e32 v59, 0xffff0000, v133
	v_pk_mul_f32 v[58:59], v[60:61], v[58:59]
	s_nop 0
	v_cvt_pk_bf16_f32 v65, v58, v59
	s_nop 0
	s_nop 0
	s_nop 0
	s_waitcnt lgkmcnt(1)
	v_mfma_f32_16x16x32_bf16 v[50:53], v[62:65], v[192:195], v[50:53]
	s_nop 0
	s_nop 0
	s_nop 0
	s_nop 4
	v_pk_mul_f32 v[52:53], v[86:87], v[52:53] op_sel_hi:[0,1]
	s_waitcnt lgkmcnt(0)
	v_mfma_f32_16x16x32_bf16 v[46:49], v[62:65], v[200:203], v[46:49]
	s_nop 0
	s_nop 0
	v_pk_mul_f32 v[50:51], v[86:87], v[50:51] op_sel_hi:[0,1]
	v_pk_fma_f32 v[124:125], v[124:125], v[78:79], v[52:53] op_sel_hi:[1,0,1]
	s_waitcnt lgkmcnt(0)
	v_mfma_f32_16x16x32_bf16 v[42:45], v[62:65], v[204:207], v[42:45]
	s_nop 0
	s_nop 0
	v_pk_fma_f32 v[126:127], v[126:127], v[78:79], v[50:51] op_sel_hi:[1,0,1]
	v_pk_mul_f32 v[48:49], v[86:87], v[48:49] op_sel_hi:[0,1]
	s_waitcnt lgkmcnt(0)
	v_mfma_f32_16x16x32_bf16 v[38:41], v[62:65], v[208:211], v[38:41]
	s_nop 0
	s_nop 0
	v_pk_mul_f32 v[46:47], v[86:87], v[46:47] op_sel_hi:[0,1]
	v_pk_mul_f32 v[44:45], v[86:87], v[44:45] op_sel_hi:[0,1]
	s_waitcnt lgkmcnt(0)
	v_mfma_f32_16x16x32_bf16 v[34:37], v[62:65], v[212:215], v[34:37]
	s_nop 0
	s_nop 0
	v_pk_mul_f32 v[42:43], v[86:87], v[42:43] op_sel_hi:[0,1]
	v_pk_mul_f32 v[40:41], v[86:87], v[40:41] op_sel_hi:[0,1]
	s_waitcnt lgkmcnt(0)
	v_mfma_f32_16x16x32_bf16 v[30:33], v[62:65], v[216:219], v[30:33]
	s_nop 0
	s_nop 0
	v_pk_mul_f32 v[38:39], v[86:87], v[38:39] op_sel_hi:[0,1]
	v_pk_mul_f32 v[36:37], v[86:87], v[36:37] op_sel_hi:[0,1]
	v_mfma_f32_16x16x32_bf16 v[54:57], v[62:65], v[196:199], v[54:57]
	v_mul_f32_e64 v34, v86, v34
	v_mul_f32_e64 v35, v86, v35
	s_nop 0
	v_pk_mul_f32 v[32:33], v[86:87], v[32:33] op_sel_hi:[0,1]
	v_pk_mul_f32 v[30:31], v[86:87], v[30:31] op_sel_hi:[0,1]
	s_waitcnt lgkmcnt(0)
	v_mfma_f32_16x16x32_bf16 v[26:29], v[62:65], v[220:223], v[26:29]
	v_fma_f32 v116, v116, v78, v48
	v_fma_f32 v117, v117, v78, v49
	v_pk_mul_f32 v[50:51], v[86:87], v[56:57] op_sel_hi:[0,1]
	v_pk_mul_f32 v[52:53], v[86:87], v[54:55] op_sel_hi:[0,1]
	v_mfma_f32_16x16x32_bf16 v[18:21], v[62:65], v[18:21], v[22:25]
	v_fma_f32 v120, v120, v78, v50
	v_fma_f32 v121, v121, v78, v51
	s_nop 0
	v_pk_mul_f32 v[28:29], v[86:87], v[28:29] op_sel_hi:[0,1]
	v_pk_mul_f32 v[26:27], v[86:87], v[26:27] op_sel_hi:[0,1]
	v_pk_fma_f32 v[122:123], v[122:123], v[78:79], v[52:53] op_sel_hi:[1,0,1]
	v_pk_fma_f32 v[118:119], v[118:119], v[78:79], v[46:47] op_sel_hi:[1,0,1]
	s_nop 0
	v_pk_mul_f32 v[20:21], v[86:87], v[20:21] op_sel_hi:[0,1]
	v_pk_mul_f32 v[18:19], v[86:87], v[18:19] op_sel_hi:[0,1]
	v_pk_fma_f32 v[112:113], v[112:113], v[78:79], v[44:45] op_sel_hi:[1,0,1]
	v_pk_fma_f32 v[114:115], v[114:115], v[78:79], v[42:43] op_sel_hi:[1,0,1]
	v_pk_fma_f32 v[108:109], v[108:109], v[78:79], v[40:41] op_sel_hi:[1,0,1]
	v_pk_fma_f32 v[110:111], v[110:111], v[78:79], v[38:39] op_sel_hi:[1,0,1]
	v_pk_fma_f32 v[104:105], v[104:105], v[78:79], v[36:37] op_sel_hi:[1,0,1]
	v_pk_fma_f32 v[106:107], v[106:107], v[78:79], v[34:35] op_sel_hi:[1,0,1]
	v_pk_fma_f32 v[100:101], v[100:101], v[78:79], v[32:33] op_sel_hi:[1,0,1]
	v_pk_fma_f32 v[102:103], v[102:103], v[78:79], v[30:31] op_sel_hi:[1,0,1]
	v_pk_fma_f32 v[98:99], v[98:99], v[78:79], v[28:29] op_sel_hi:[1,0,1]
	v_pk_fma_f32 v[96:97], v[96:97], v[78:79], v[26:27] op_sel_hi:[1,0,1]
	v_pk_fma_f32 v[76:77], v[76:77], v[78:79], v[20:21] op_sel_hi:[1,0,1]
	v_pk_fma_f32 v[74:75], v[74:75], v[78:79], v[18:19] op_sel_hi:[1,0,1]
	s_cbranch_scc1 .LBB0_494

.LBB0_490:
	s_or_b64 exec, exec, s[18:19]
	v_add_u32_e32 v145, 0, v147
	s_waitcnt lgkmcnt(0)
	s_barrier
	ds_read_b128 v[18:21], v145 offset:34816
	ds_read_b128 v[22:25], v145 offset:34832
	ds_read_b64_tr_b16 v[26:27], v137
	ds_read_b64_tr_b16 v[28:29], v137 offset:1088
	ds_read_b64_tr_b16 v[160:161], v144 offset:17408
	ds_read_b64_tr_b16 v[162:163], v144 offset:18496
	ds_read_b64_tr_b16 v[164:165], v144 offset:17440
	ds_read_b64_tr_b16 v[166:167], v144 offset:18528
	ds_read_b64_tr_b16 v[168:169], v144 offset:17472
	ds_read_b64_tr_b16 v[170:171], v144 offset:18560
	ds_read_b64_tr_b16 v[172:173], v144 offset:17504
	ds_read_b64_tr_b16 v[174:175], v144 offset:18592
	ds_read_b64_tr_b16 v[176:177], v144 offset:17536
	ds_read_b64_tr_b16 v[178:179], v144 offset:18624
	s_waitcnt vmcnt(11)
	v_lshlrev_b32_e32 v78, 16, v73
	v_and_b32_e32 v86, 0xffff0000, v73
	s_waitcnt lgkmcnt(11)
	v_lshlrev_b32_e32 v30, 16, v26
	v_and_b32_e32 v31, 0xffff0000, v26
	v_pk_mul_f32 v[18:19], v[18:19], v[30:31]
	s_nop 0
	v_cvt_pk_bf16_f32 v26, v18, v19
	v_lshlrev_b32_e32 v18, 16, v27
	v_and_b32_e32 v19, 0xffff0000, v27
	v_pk_mul_f32 v[18:19], v[20:21], v[18:19]
	s_nop 0
	v_cvt_pk_bf16_f32 v27, v18, v19
	s_waitcnt lgkmcnt(10)
	v_lshlrev_b32_e32 v18, 16, v28
	v_and_b32_e32 v19, 0xffff0000, v28
	v_pk_mul_f32 v[18:19], v[22:23], v[18:19]
	s_nop 0
	v_cvt_pk_bf16_f32 v28, v18, v19
	v_lshlrev_b32_e32 v18, 16, v29
	v_and_b32_e32 v19, 0xffff0000, v29
	v_pk_mul_f32 v[18:19], v[24:25], v[18:19]
	s_nop 0
	v_cvt_pk_bf16_f32 v29, v18, v19
	ds_read_b64_tr_b16 v[180:181], v144 offset:17568
	ds_read_b64_tr_b16 v[182:183], v144 offset:18656
	ds_read_b64_tr_b16 v[184:185], v144 offset:17600
	ds_read_b64_tr_b16 v[186:187], v144 offset:18688
	ds_read_b64_tr_b16 v[188:189], v144 offset:17632
	ds_read_b64_tr_b16 v[190:191], v144 offset:18720
	s_waitcnt lgkmcnt(14)
	v_mfma_f32_16x16x32_bf16 v[54:57], v[26:29], v[160:163], 0
	ds_read_b64_tr_b16 v[192:193], v144 offset:26112
	ds_read_b64_tr_b16 v[194:195], v144 offset:27200
	s_waitcnt lgkmcnt(12)
	v_mfma_f32_16x16x32_bf16 v[46:49], v[26:29], v[168:171], 0
	ds_read_b64_tr_b16 v[196:197], v144 offset:26144
	ds_read_b64_tr_b16 v[198:199], v144 offset:27232
	s_waitcnt lgkmcnt(12)
	v_mfma_f32_16x16x32_bf16 v[42:45], v[26:29], v[172:175], 0
	ds_read_b64_tr_b16 v[200:201], v144 offset:26176
	ds_read_b64_tr_b16 v[202:203], v144 offset:27264
	s_waitcnt lgkmcnt(12)
	v_mfma_f32_16x16x32_bf16 v[38:41], v[26:29], v[176:179], 0
	ds_read_b64_tr_b16 v[204:205], v144 offset:26208
	ds_read_b64_tr_b16 v[206:207], v144 offset:27296
	s_waitcnt lgkmcnt(12)
	v_mfma_f32_16x16x32_bf16 v[34:37], v[26:29], v[180:183], 0
	ds_read_b64_tr_b16 v[208:209], v144 offset:26240
	ds_read_b64_tr_b16 v[210:211], v144 offset:27328
	s_waitcnt lgkmcnt(12)
	v_mfma_f32_16x16x32_bf16 v[30:33], v[26:29], v[184:187], 0
	ds_read_b64_tr_b16 v[212:213], v144 offset:26272
	ds_read_b64_tr_b16 v[214:215], v144 offset:27360
	ds_read_b64_tr_b16 v[216:217], v144 offset:26304
	ds_read_b64_tr_b16 v[218:219], v144 offset:27392
	ds_read_b64_tr_b16 v[220:221], v144 offset:26336
	ds_read_b64_tr_b16 v[222:223], v144 offset:27424
	ds_read_b128 v[62:65], v145 offset:34944
	ds_read_b128 v[58:61], v145 offset:34960
	ds_read_b64_tr_b16 v[150:151], v137 offset:8704
	ds_read_b64_tr_b16 v[152:153], v137 offset:9792
	s_waitcnt lgkmcnt(1)
	v_lshlrev_b32_e32 v154, 16, v150
	v_and_b32_e32 v155, 0xffff0000, v150
	v_lshlrev_b32_e32 v150, 16, v151
	v_and_b32_e32 v151, 0xffff0000, v151
	v_pk_mul_f32 v[62:63], v[62:63], v[154:155]
	v_pk_mul_f32 v[64:65], v[64:65], v[150:151]
	v_cvt_pk_bf16_f32 v62, v62, v63
	v_cvt_pk_bf16_f32 v63, v64, v65
	s_waitcnt lgkmcnt(0)
	v_lshlrev_b32_e32 v64, 16, v152
	v_and_b32_e32 v65, 0xffff0000, v152
	v_pk_mul_f32 v[58:59], v[58:59], v[64:65]
	v_mfma_f32_16x16x32_bf16 v[50:53], v[26:29], v[164:167], 0
	v_cvt_pk_bf16_f32 v64, v58, v59
	v_lshlrev_b32_e32 v58, 16, v153
	v_and_b32_e32 v59, 0xffff0000, v153
	v_pk_mul_f32 v[58:59], v[60:61], v[58:59]
	v_mov_b64_e32 v[24:25], s[6:7]
	v_cvt_pk_bf16_f32 v65, v58, v59
	s_nop 0
	s_nop 0
	s_waitcnt lgkmcnt(0)
	v_mfma_f32_16x16x32_bf16 v[54:57], v[62:65], v[192:195], v[54:57]
	s_nop 0
	s_nop 0
	v_mov_b64_e32 v[22:23], s[4:5]
	s_waitcnt lgkmcnt(0)
	v_mfma_f32_16x16x32_bf16 v[50:53], v[62:65], v[196:199], v[50:53]
	s_nop 0
	s_nop 0
	s_waitcnt lgkmcnt(0)
	v_mfma_f32_16x16x32_bf16 v[46:49], v[62:65], v[200:203], v[46:49]
	s_nop 0
	s_nop 0
	s_waitcnt lgkmcnt(0)
	v_mfma_f32_16x16x32_bf16 v[42:45], v[62:65], v[204:207], v[42:45]
	s_nop 0
	s_nop 0
	s_waitcnt lgkmcnt(0)
	v_mfma_f32_16x16x32_bf16 v[38:41], v[62:65], v[208:211], v[38:41]
	s_nop 0
	s_nop 0
	s_waitcnt lgkmcnt(0)
	v_mfma_f32_16x16x32_bf16 v[34:37], v[62:65], v[212:215], v[34:37]
	s_nop 0
	s_nop 0
	s_waitcnt lgkmcnt(0)
; #define LAS __attribute__((address_space(3)))
; __device__ __forceinline__ f32x4 bf4_to_f32(u32x2 w) { return (f32x4){bflo(w.x), bfhi(w.x), bflo(w.y), bfhi(w.y)}; }
; __device__ __forceinline__ u32x2 f32_to_bf4(f32x4 v) { u32x2 w; w.x = cvtpk(v[0], v[1]); w.y = cvtpk(v[2], v[3]); return w; }
; __device__ __forceinline__ void ml_stage_k(LAS unsigned char* lds, int offK, const LAS float* WL, const u32x2 (&xr)[4], int cg, int ts) {
;     f32x4 wk[4];
; #pragma unroll
;     for (int j = 0; j < 4; ++j) wk[j] = *(const LAS f32x4*)(WL + WL_WK + (cg * 4 + j) * 4);
; #pragma unroll
;     for (int i = 0; i < 4; ++i) { const f32x4 xc = bf4_to_f32(xr[i]);
;         const f32x4 k = wk[0] * xc[0] + wk[1] * xc[1] + wk[2] * xc[2] + wk[3] * xc[3];
;         *(LAS u32x2*)(lds + offK + (4 * ts + i) * GP128 + 8 * cg) = f32_to_bf4(k); }
	v_mfma_f32_16x16x32_bf16 v[30:33], v[62:65], v[216:219], v[30:33]
	s_nop 0
	s_nop 0
	v_mfma_f32_16x16x32_bf16 v[18:21], v[26:29], v[188:191], 0
	v_mfma_f32_16x16x32_bf16 v[26:29], v[26:29], v[22:25], 0
	s_waitcnt lgkmcnt(0)
	v_mfma_f32_16x16x32_bf16 v[58:61], v[62:65], v[220:223], v[18:21]
	v_mfma_f32_16x16x32_bf16 v[18:21], v[62:65], v[22:25], v[26:29]
	v_mov_b32_e32 v22, s20
	ds_read_b64 v[22:23], v22 offset:8
	s_nop 2
	ds_read_b128 v[24:27], v140 offset:39936
	ds_read_b128 v[62:65], v140 offset:39952
	ds_read_b128 v[150:153], v140 offset:39968
	ds_read_b128 v[154:157], v140 offset:39984
	v_lshlrev_b32_e32 v28, 16, v72
	v_and_b32_e32 v72, 0xffff0000, v72
	s_waitcnt lgkmcnt(2)
	v_pk_mul_f32 v[158:159], v[72:73], v[64:65] op_sel_hi:[0,1]
	v_pk_mul_f32 v[72:73], v[72:73], v[62:63] op_sel_hi:[0,1]
	v_pk_fma_f32 v[158:159], v[28:29], v[26:27], v[158:159] op_sel_hi:[0,1,1]
	v_pk_fma_f32 v[28:29], v[28:29], v[24:25], v[72:73] op_sel_hi:[0,1,1]
	s_waitcnt vmcnt(0) lgkmcnt(1)
	v_pk_fma_f32 v[28:29], v[78:79], v[150:151], v[28:29] op_sel_hi:[0,1,1]
	v_pk_fma_f32 v[72:73], v[78:79], v[152:153], v[158:159] op_sel_hi:[0,1,1]
	s_waitcnt lgkmcnt(0)
	v_pk_fma_f32 v[72:73], v[86:87], v[156:157], v[72:73] op_sel_hi:[0,1,1]
	v_pk_fma_f32 v[28:29], v[86:87], v[154:155], v[28:29] op_sel_hi:[0,1,1]
	v_cvt_pk_bf16_f32 v28, v28, v29
	v_cvt_pk_bf16_f32 v29, v72, v73
	v_lshlrev_b32_e32 v72, 16, v70
	v_and_b32_e32 v70, 0xffff0000, v70
	v_lshlrev_b32_e32 v78, 16, v71
	v_and_b32_e32 v86, 0xffff0000, v71
	v_pk_mul_f32 v[158:159], v[70:71], v[64:65] op_sel_hi:[0,1]
	v_pk_mul_f32 v[70:71], v[70:71], v[62:63] op_sel_hi:[0,1]
	v_pk_fma_f32 v[158:159], v[72:73], v[26:27], v[158:159] op_sel_hi:[0,1,1]
	v_pk_fma_f32 v[70:71], v[72:73], v[24:25], v[70:71] op_sel_hi:[0,1,1]
	v_pk_fma_f32 v[70:71], v[78:79], v[150:151], v[70:71] op_sel_hi:[0,1,1]
	v_pk_fma_f32 v[72:73], v[78:79], v[152:153], v[158:159] op_sel_hi:[0,1,1]
	v_pk_fma_f32 v[72:73], v[86:87], v[156:157], v[72:73] op_sel_hi:[0,1,1]
	v_pk_fma_f32 v[70:71], v[86:87], v[154:155], v[70:71] op_sel_hi:[0,1,1]
	v_cvt_pk_bf16_f32 v70, v70, v71
	v_cvt_pk_bf16_f32 v71, v72, v73
	v_add_u32_e32 v73, 0xb000, v143
	ds_write2_b64 v73, v[28:29], v[70:71] offset1:34
	v_lshlrev_b32_e32 v28, 16, v68
	v_and_b32_e32 v68, 0xffff0000, v68
	v_lshlrev_b32_e32 v70, 16, v69
	v_and_b32_e32 v72, 0xffff0000, v69
	v_pk_mul_f32 v[158:159], v[68:69], v[64:65] op_sel_hi:[0,1]
	v_pk_mul_f32 v[68:69], v[68:69], v[62:63] op_sel_hi:[0,1]
	v_pk_fma_f32 v[158:159], v[28:29], v[26:27], v[158:159] op_sel_hi:[0,1,1]
	v_pk_fma_f32 v[28:29], v[28:29], v[24:25], v[68:69] op_sel_hi:[0,1,1]
	v_pk_fma_f32 v[28:29], v[70:71], v[150:151], v[28:29] op_sel_hi:[0,1,1]
	v_pk_fma_f32 v[68:69], v[70:71], v[152:153], v[158:159] op_sel_hi:[0,1,1]
	v_pk_fma_f32 v[68:69], v[72:73], v[156:157], v[68:69] op_sel_hi:[0,1,1]
	v_pk_fma_f32 v[28:29], v[72:73], v[154:155], v[28:29] op_sel_hi:[0,1,1]
	v_cvt_pk_bf16_f32 v28, v28, v29
	v_cvt_pk_bf16_f32 v29, v68, v69
	v_lshlrev_b32_e32 v68, 16, v66
	v_and_b32_e32 v66, 0xffff0000, v66
	v_pk_mul_f32 v[64:65], v[66:67], v[64:65] op_sel_hi:[0,1]
	v_pk_mul_f32 v[62:63], v[66:67], v[62:63] op_sel_hi:[0,1]
	v_lshlrev_b32_e32 v70, 16, v67
	v_pk_fma_f32 v[26:27], v[68:69], v[26:27], v[64:65] op_sel_hi:[0,1,1]
	v_pk_fma_f32 v[24:25], v[68:69], v[24:25], v[62:63] op_sel_hi:[0,1,1]
	v_and_b32_e32 v72, 0xffff0000, v67
	v_pk_fma_f32 v[24:25], v[70:71], v[150:151], v[24:25] op_sel_hi:[0,1,1]
	v_pk_fma_f32 v[26:27], v[70:71], v[152:153], v[26:27] op_sel_hi:[0,1,1]
	v_pk_fma_f32 v[26:27], v[72:73], v[156:157], v[26:27] op_sel_hi:[0,1,1]
	v_pk_fma_f32 v[24:25], v[72:73], v[154:155], v[24:25] op_sel_hi:[0,1,1]
	v_cvt_pk_bf16_f32 v24, v24, v25
	v_cvt_pk_bf16_f32 v25, v26, v27
	ds_write2_b64 v73, v[28:29], v[24:25] offset0:68 offset1:102
	ds_write_b128 v141, v[2:5] offset:62464
	ds_write_b128 v142, v[6:9] offset:8704
	s_and_saveexec_b64 s[18:19], s[2:3]
	ds_write_b32 v139, v138
	s_or_b64 exec, exec, s[18:19]
	v_add_co_u32_e32 v2, vcc, 0x30000, v132
	s_nop 1
	v_addc_co_u32_e32 v3, vcc, 0, v133, vcc
	global_load_dwordx2 v[72:73], v[2:3], off
	global_load_dwordx2 v[70:71], v[2:3], off offset:1024
	global_load_dwordx2 v[68:69], v[2:3], off offset:2048
	global_load_dwordx2 v[66:67], v[2:3], off offset:3072
	v_add_co_u32_e32 v2, vcc, 0x1030000, v130
	s_nop 1
	v_addc_co_u32_e32 v3, vcc, 0, v131, vcc
	v_add_co_u32_e32 v6, vcc, 0x1038000, v130
	s_nop 1
	v_addc_co_u32_e32 v7, vcc, 0, v131, vcc
	global_load_dwordx4 v[2:5], v[2:3], off
	s_nop 0
	global_load_dwordx4 v[6:9], v[6:7], off
	s_and_saveexec_b64 s[18:19], s[2:3]
	s_cbranch_execz .LBB0_485
	global_load_dword v138, v[90:91], off
	s_branch .LBB0_485
